# RG-LRU latency-chain consolidation: stage-3/stage-5 LDS read batching + stage-4 carry via upfront reads and v_cndmask + folded canonicalising v_max, all together
# baseline (speedup 1.0000x reference)
; __device__ __forceinline__ float bf2f(bf16_t v) { return __uint_as_float(((unsigned)v) << 16); }
; __device__ __forceinline__ float sigmoidf_(float x) { return __builtin_amdgcn_rcpf(1.f + __expf(-x)); }
; #define MFMA16(a, b, c) __builtin_amdgcn_mfma_f32_16x16x32_bf16((a), (b), (c), 0, 0, 0)
; __device__ __forceinline__ void rglru_unit(const Params& p, const WS& ws, int j, int u, bool dry = false) {
;     ...
; #pragma unroll
;       for (int ks = 0; ks < 4; ++ks) {
;         const bf16x8 xf = *(const bf16x8*)(XC + (16 * w + lr) * 136 + 32 * ks + 8 * lq);
; #pragma unroll
;         for (int gate = 0; gate < 2; ++gate)
; #pragma unroll
;           for (int mt = 0; mt < 2; ++mt) {
;             const bf16x8 wf = *(const bf16x8*)(WG + (gate * 32 + 16 * mt + lr) * 136 + 32 * ks + 8 * lq);
;             ga_[gate][mt] = MFMA16(wf, xf, ga_[gate][mt]);
;           }
;       }
;       const int tok = 16 * w + lr;
; #pragma unroll
;       for (int mt = 0; mt < 2; ++mt)
; #pragma unroll
;         for (int jj = 0; jj < 4; ++jj) {
;           const int n = 16 * mt + 4 * lq + jj;
;           const float xcv = bf2f(XC[tok * 136 + 32 * jq + n]);
;           const float r = sigmoidf_(ga_[0][mt][jj] + ba[mt][jj]);
;           const float ig = sigmoidf_(ga_[1][mt][jj] + bx[mt][jj]);
;           const float la = -r * sp[mt][jj];
;           const float a = __expf(la);
;           const float x2 = 2.f * la;
;           const float om = x2 > -0.02f ? -x2 * (1.f + 0.5f * x2 * (1.f + x2 * (1.f / 3.f))) : 1.f - a * a;
;           const float mult = __builtin_amdgcn_sqrtf(fmaxf(om, 0.f));
;           AUa[tok * 33 + n] = a;
;           AUu[tok * 33 + n] = mult * ig * xcv;
;         }
.LBB0_1420:
	ds_read_b128 v[52:55], v111
	ds_read_b128 v[56:59], v112 offset:17408
	ds_read_b128 v[60:63], v112 offset:21760
	ds_read_b128 v[64:67], v112 offset:26112
	ds_read_b128 v[136:139], v112 offset:30464
	ds_read_b128 v[212:215], v111 offset:64
	ds_read_b128 v[216:219], v111 offset:128
	ds_read_b128 v[220:223], v111 offset:192
	ds_read_b128 v[224:227], v112 offset:17472
	ds_read_b128 v[228:231], v112 offset:21824
	ds_read_b128 v[232:235], v112 offset:26176
	ds_read_b128 v[244:247], v112 offset:30528
	ds_read_b128 v[248:251], v112 offset:17536
	ds_read_b128 v[252:255], v112 offset:21888
	s_waitcnt lgkmcnt(12)
	v_mfma_f32_16x16x32_bf16 v[56:59], v[56:59], v[52:55], 0
	s_waitcnt lgkmcnt(11)
	v_mfma_f32_16x16x32_bf16 v[60:63], v[60:63], v[52:55], 0
	s_waitcnt lgkmcnt(10)
	v_mfma_f32_16x16x32_bf16 v[64:67], v[64:67], v[52:55], 0
	s_waitcnt lgkmcnt(9)
	v_mfma_f32_16x16x32_bf16 v[52:55], v[136:139], v[52:55], 0
	s_nop 0
	s_nop 0
	s_waitcnt lgkmcnt(5)
	v_mfma_f32_16x16x32_bf16 v[56:59], v[224:227], v[212:215], v[56:59]
	ds_read_b128 v[224:227], v112 offset:26240
	s_nop 0
	s_waitcnt lgkmcnt(5)
	v_mfma_f32_16x16x32_bf16 v[60:63], v[228:231], v[212:215], v[60:63]
	ds_read_b128 v[228:231], v112 offset:30592
	s_nop 0
	s_waitcnt lgkmcnt(5)
	v_mfma_f32_16x16x32_bf16 v[64:67], v[232:235], v[212:215], v[64:67]
	ds_read_b128 v[232:235], v112 offset:17600
	s_nop 0
	s_waitcnt lgkmcnt(5)
	v_mfma_f32_16x16x32_bf16 v[52:55], v[244:247], v[212:215], v[52:55]
	ds_read_b128 v[244:247], v112 offset:21952
	s_nop 0
	s_nop 0
	s_waitcnt lgkmcnt(5)
	v_mfma_f32_16x16x32_bf16 v[56:59], v[248:251], v[216:219], v[56:59]
	ds_read_b128 v[248:251], v112 offset:26304
	s_nop 0
	s_waitcnt lgkmcnt(5)
	v_mfma_f32_16x16x32_bf16 v[60:63], v[252:255], v[216:219], v[60:63]
	ds_read_b128 v[252:255], v112 offset:30656
	s_nop 0
	s_waitcnt lgkmcnt(5)
	v_mfma_f32_16x16x32_bf16 v[140:143], v[224:227], v[216:219], v[64:67]
	s_nop 2
	s_nop 0
	s_waitcnt lgkmcnt(4)
	v_mfma_f32_16x16x32_bf16 v[52:55], v[228:231], v[216:219], v[52:55]
	s_nop 0
	s_nop 0
	ds_read_u16 v13, v113
	s_waitcnt lgkmcnt(4)
	v_mfma_f32_16x16x32_bf16 v[64:67], v[232:235], v[220:223], v[56:59]
	s_nop 2
	s_nop 0
	s_waitcnt lgkmcnt(3)
	v_mfma_f32_16x16x32_bf16 v[56:59], v[244:247], v[220:223], v[60:63]
	s_nop 2
	s_nop 0
	v_add_f32_e32 v14, v0, v64
	v_mul_f32_e32 v14, 0xbfb8aa3b, v14
	v_exp_f32_e32 v14, v14
	s_waitcnt lgkmcnt(2)
	v_mfma_f32_16x16x32_bf16 v[60:63], v[248:251], v[220:223], v[140:143]
	s_nop 2
	s_nop 0
	v_add_f32_e32 v14, 1.0, v14
	v_rcp_f32_e64 v14, -v14
	s_waitcnt lgkmcnt(0)
	v_mfma_f32_16x16x32_bf16 v[52:55], v[252:255], v[220:223], v[52:55]
	v_mul_f32_e32 v14, v89, v14
	v_mul_f32_e32 v15, 0x3fb8aa3b, v14
	v_exp_f32_e32 v15, v15
	v_add_f32_e32 v14, v14, v14
	v_cmp_nlt_f32_e64 s[52:53], s29, v14
	s_and_saveexec_b64 s[4:5], s[52:53]
	s_xor_b64 s[4:5], exec, s[4:5]
	v_fma_f32 v64, -v15, v15, 1.0
	s_andn2_saveexec_b64 s[4:5], s[4:5]
	v_pk_mul_f32 v[136:137], v[14:15], s[88:89] op_sel_hi:[0,1]
	v_add_f32_e32 v64, 1.0, v137
	v_fma_f32 v64, v136, v64, 1.0
	v_mul_f32_e64 v64, v64, -v14
	s_or_b64 exec, exec, s[4:5]
	v_add_f32_e32 v14, v8, v60
	v_max_f32_e32 v60, v64, v64
	v_add_f32_e32 v64, v1, v65
	v_mul_f32_e32 v14, 0xbfb8aa3b, v14
	v_mul_f32_e32 v64, 0xbfb8aa3b, v64
	v_exp_f32_e32 v14, v14
	v_exp_f32_e32 v64, v64
	v_max_f32_e32 v60, 0, v60
	v_sqrt_f32_e32 v60, v60
	v_add_f32_e32 v14, 1.0, v14
	v_add_f32_e32 v64, 1.0, v64
	v_rcp_f32_e32 v14, v14
	v_rcp_f32_e64 v64, -v64
	v_lshlrev_b32_e32 v13, 16, v13
	v_mul_f32_e32 v14, v14, v60
	v_mul_f32_e32 v64, v93, v64
	v_mul_f32_e32 v14, v14, v13
	ds_read_u16 v60, v113 offset:2
	v_mul_f32_e32 v13, 0x3fb8aa3b, v64
	v_exp_f32_e32 v13, v13
	ds_write2st64_b32 v72, v15, v14 offset0:136 offset1:169
	v_add_f32_e32 v14, v64, v64
	v_cmp_nlt_f32_e64 s[52:53], s29, v14
	s_and_saveexec_b64 s[4:5], s[52:53]
	s_xor_b64 s[4:5], exec, s[4:5]
	v_fma_f32 v15, -v13, v13, 1.0
	s_andn2_saveexec_b64 s[4:5], s[4:5]
	v_pk_mul_f32 v[64:65], v[14:15], s[88:89] op_sel_hi:[0,1]
	v_add_f32_e32 v15, 1.0, v65
	v_fma_f32 v15, v64, v15, 1.0
	v_mul_f32_e64 v15, v15, -v14
	s_or_b64 exec, exec, s[4:5]
	s_waitcnt lgkmcnt(1)
	v_lshlrev_b32_e32 v14, 16, v60
	v_add_f32_e32 v60, v9, v61
	v_mul_f32_e32 v60, 0xbfb8aa3b, v60
	v_exp_f32_e32 v60, v60
	v_max_f32_e32 v15, 0, v15
	v_sqrt_f32_e32 v15, v15
	v_add_f32_e32 v60, 1.0, v60
	v_rcp_f32_e32 v60, v60
	v_add_u32_e32 v135, 4, v72
	v_mul_f32_e32 v15, v60, v15
	v_mul_f32_e32 v14, v15, v14
	ds_write2st64_b32 v135, v13, v14 offset0:136 offset1:169
	v_add_f32_e32 v14, v2, v66
	v_mul_f32_e32 v14, 0xbfb8aa3b, v14
	v_exp_f32_e32 v14, v14
	ds_read_u16 v13, v113 offset:4
	v_add_f32_e32 v14, 1.0, v14
	v_rcp_f32_e64 v14, -v14
	s_nop 0
	v_mul_f32_e32 v14, v95, v14
	v_mul_f32_e32 v15, 0x3fb8aa3b, v14
	v_exp_f32_e32 v15, v15
	v_add_f32_e32 v14, v14, v14
	v_cmp_nlt_f32_e64 s[52:53], s29, v14
	s_and_saveexec_b64 s[4:5], s[52:53]
	s_xor_b64 s[4:5], exec, s[4:5]
	v_fma_f32 v60, -v15, v15, 1.0
	s_andn2_saveexec_b64 s[4:5], s[4:5]
	v_pk_mul_f32 v[60:61], v[14:15], s[88:89] op_sel_hi:[0,1]
	v_add_f32_e32 v61, 1.0, v61
	v_fma_f32 v60, v60, v61, 1.0
	v_mul_f32_e64 v60, v60, -v14
	s_or_b64 exec, exec, s[4:5]
	v_add_f32_e32 v14, v10, v62
	v_mul_f32_e32 v14, 0xbfb8aa3b, v14
	v_exp_f32_e32 v14, v14
	v_max_f32_e32 v60, 0, v60
	v_sqrt_f32_e32 v60, v60
	v_add_f32_e32 v14, 1.0, v14
	v_rcp_f32_e32 v14, v14
	s_waitcnt lgkmcnt(0)
; __device__ __forceinline__ float bf2f(bf16_t v) { return __uint_as_float(((unsigned)v) << 16); }
; __device__ __forceinline__ float sigmoidf_(float x) { return __builtin_amdgcn_rcpf(1.f + __expf(-x)); }
; __device__ __forceinline__ void rglru_unit(const Params& p, const WS& ws, int j, int u, bool dry = false) {
;     ...
;       const int tok = 16 * w + lr;
; #pragma unroll
;       for (int mt = 0; mt < 2; ++mt)
; #pragma unroll
;         for (int jj = 0; jj < 4; ++jj) {
;           const int n = 16 * mt + 4 * lq + jj;
;           const float xcv = bf2f(XC[tok * 136 + 32 * jq + n]);
;           const float r = sigmoidf_(ga_[0][mt][jj] + ba[mt][jj]);
;           const float ig = sigmoidf_(ga_[1][mt][jj] + bx[mt][jj]);
;           const float la = -r * sp[mt][jj];
;           const float a = __expf(la);
;           const float x2 = 2.f * la;
;           const float om = x2 > -0.02f ? -x2 * (1.f + 0.5f * x2 * (1.f + x2 * (1.f / 3.f))) : 1.f - a * a;
;           const float mult = __builtin_amdgcn_sqrtf(fmaxf(om, 0.f));
;           AUa[tok * 33 + n] = a;
;           AUu[tok * 33 + n] = mult * ig * xcv;
;         }
;     }
;     __syncthreads();
	v_lshlrev_b32_e32 v13, 16, v13
	v_add_u32_e32 v136, 8, v72
	v_mul_f32_e32 v14, v14, v60
	v_mul_f32_e32 v13, v14, v13
	v_add_f32_e32 v14, v3, v67
	v_mul_f32_e32 v14, 0xbfb8aa3b, v14
	v_exp_f32_e32 v14, v14
	ds_write2st64_b32 v136, v15, v13 offset0:136 offset1:169
	ds_read_u16 v13, v113 offset:6
	v_add_f32_e32 v14, 1.0, v14
	v_rcp_f32_e64 v14, -v14
	s_nop 0
	v_mul_f32_e32 v14, v96, v14
	v_mul_f32_e32 v15, 0x3fb8aa3b, v14
	v_exp_f32_e32 v15, v15
	v_add_f32_e32 v14, v14, v14
	v_cmp_nlt_f32_e64 s[52:53], s29, v14
	s_and_saveexec_b64 s[4:5], s[52:53]
	s_xor_b64 s[4:5], exec, s[4:5]
	v_fma_f32 v60, -v15, v15, 1.0
	s_andn2_saveexec_b64 s[4:5], s[4:5]
	v_pk_mul_f32 v[60:61], v[14:15], s[88:89] op_sel_hi:[0,1]
	v_add_f32_e32 v61, 1.0, v61
	v_fma_f32 v60, v60, v61, 1.0
	v_mul_f32_e64 v60, v60, -v14
	s_or_b64 exec, exec, s[4:5]
	v_add_f32_e32 v14, v11, v63
	v_mul_f32_e32 v14, 0xbfb8aa3b, v14
	v_exp_f32_e32 v14, v14
	v_max_f32_e32 v60, 0, v60
	v_sqrt_f32_e32 v60, v60
	v_add_f32_e32 v14, 1.0, v14
	v_rcp_f32_e32 v14, v14
	s_waitcnt lgkmcnt(0)
	v_lshlrev_b32_e32 v13, 16, v13
	v_add_u32_e32 v139, 12, v72
	v_mul_f32_e32 v14, v14, v60
	v_mul_f32_e32 v13, v14, v13
	v_add_f32_e32 v14, v4, v56
	v_mul_f32_e32 v14, 0xbfb8aa3b, v14
	v_exp_f32_e32 v14, v14
	ds_write2st64_b32 v139, v15, v13 offset0:136 offset1:169
	ds_read_u16 v13, v113 offset:32
	v_add_f32_e32 v14, 1.0, v14
	v_rcp_f32_e64 v14, -v14
	s_nop 0
	v_mul_f32_e32 v14, v97, v14
	v_mul_f32_e32 v15, 0x3fb8aa3b, v14
	v_exp_f32_e32 v15, v15
	v_add_f32_e32 v14, v14, v14
	v_cmp_nlt_f32_e64 s[52:53], s29, v14
	s_and_saveexec_b64 s[4:5], s[52:53]
	s_xor_b64 s[4:5], exec, s[4:5]
	v_fma_f32 v56, -v15, v15, 1.0
	s_andn2_saveexec_b64 s[4:5], s[4:5]
	v_pk_mul_f32 v[60:61], v[14:15], s[88:89] op_sel_hi:[0,1]
	v_add_f32_e32 v56, 1.0, v61
	v_fma_f32 v56, v60, v56, 1.0
	v_mul_f32_e64 v56, v56, -v14
	s_or_b64 exec, exec, s[4:5]
	v_add_f32_e32 v14, v16, v52
	v_mul_f32_e32 v14, 0xbfb8aa3b, v14
	v_exp_f32_e32 v14, v14
	v_max_f32_e32 v52, 0, v56
	v_sqrt_f32_e32 v52, v52
	v_add_f32_e32 v14, 1.0, v14
	v_rcp_f32_e32 v14, v14
	s_waitcnt lgkmcnt(0)
	v_lshlrev_b32_e32 v13, 16, v13
	v_add_u32_e32 v141, 64, v72
	v_mul_f32_e32 v14, v14, v52
	v_mul_f32_e32 v13, v14, v13
	v_add_f32_e32 v14, v5, v57
	v_mul_f32_e32 v14, 0xbfb8aa3b, v14
	v_exp_f32_e32 v14, v14
	ds_write2st64_b32 v141, v15, v13 offset0:136 offset1:169
	ds_read_u16 v13, v113 offset:34
	v_add_f32_e32 v14, 1.0, v14
	v_rcp_f32_e64 v14, -v14
	s_nop 0
	v_mul_f32_e32 v14, v98, v14
	v_mul_f32_e32 v15, 0x3fb8aa3b, v14
	v_exp_f32_e32 v15, v15
	v_add_f32_e32 v14, v14, v14
	v_cmp_nlt_f32_e64 s[52:53], s29, v14
	s_and_saveexec_b64 s[4:5], s[52:53]
	s_xor_b64 s[4:5], exec, s[4:5]
	v_fma_f32 v52, -v15, v15, 1.0
	s_andn2_saveexec_b64 s[4:5], s[4:5]
	v_pk_mul_f32 v[56:57], v[14:15], s[88:89] op_sel_hi:[0,1]
	v_add_f32_e32 v52, 1.0, v57
	v_fma_f32 v52, v56, v52, 1.0
	v_mul_f32_e64 v52, v52, -v14
	s_or_b64 exec, exec, s[4:5]
	v_add_f32_e32 v14, v17, v53
	v_mul_f32_e32 v14, 0xbfb8aa3b, v14
	v_exp_f32_e32 v14, v14
	v_max_f32_e32 v52, 0, v52
	v_sqrt_f32_e32 v52, v52
	v_add_f32_e32 v14, 1.0, v14
	v_rcp_f32_e32 v14, v14
	s_waitcnt lgkmcnt(0)
	v_lshlrev_b32_e32 v13, 16, v13
	v_add_u32_e32 v142, 0x44, v72
	v_mul_f32_e32 v14, v14, v52
	v_mul_f32_e32 v13, v14, v13
	v_add_f32_e32 v14, v6, v58
	v_mul_f32_e32 v14, 0xbfb8aa3b, v14
	v_exp_f32_e32 v14, v14
	ds_write2st64_b32 v142, v15, v13 offset0:136 offset1:169
	ds_read_u16 v13, v113 offset:36
	v_add_f32_e32 v14, 1.0, v14
	v_rcp_f32_e64 v14, -v14
	s_nop 0
	v_mul_f32_e32 v14, v99, v14
	v_mul_f32_e32 v15, 0x3fb8aa3b, v14
	v_exp_f32_e32 v15, v15
	v_add_f32_e32 v14, v14, v14
	v_cmp_nlt_f32_e64 s[52:53], s29, v14
	s_and_saveexec_b64 s[4:5], s[52:53]
	s_xor_b64 s[4:5], exec, s[4:5]
	v_fma_f32 v52, -v15, v15, 1.0
	s_andn2_saveexec_b64 s[4:5], s[4:5]
	v_pk_mul_f32 v[52:53], v[14:15], s[88:89] op_sel_hi:[0,1]
	v_add_f32_e32 v53, 1.0, v53
	v_fma_f32 v52, v52, v53, 1.0
	v_mul_f32_e64 v52, v52, -v14
	s_or_b64 exec, exec, s[4:5]
	v_add_f32_e32 v14, v18, v54
	v_mul_f32_e32 v14, 0xbfb8aa3b, v14
	v_exp_f32_e32 v14, v14
	v_max_f32_e32 v52, 0, v52
	v_sqrt_f32_e32 v52, v52
	v_add_f32_e32 v14, 1.0, v14
	v_rcp_f32_e32 v14, v14
	s_waitcnt lgkmcnt(0)
	v_lshlrev_b32_e32 v13, 16, v13
	v_add_u32_e32 v144, 0x48, v72
	v_mul_f32_e32 v14, v14, v52
	v_mul_f32_e32 v13, v14, v13
	v_add_f32_e32 v14, v7, v59
	v_mul_f32_e32 v14, 0xbfb8aa3b, v14
	v_exp_f32_e32 v14, v14
	ds_write2st64_b32 v144, v15, v13 offset0:136 offset1:169
	ds_read_u16 v13, v113 offset:38
	v_add_f32_e32 v14, 1.0, v14
	v_rcp_f32_e64 v14, -v14
	s_nop 0
	v_mul_f32_e32 v14, v105, v14
	v_mul_f32_e32 v15, 0x3fb8aa3b, v14
	v_exp_f32_e32 v15, v15
	v_add_f32_e32 v14, v14, v14
	v_cmp_nlt_f32_e64 s[52:53], s29, v14
	s_and_saveexec_b64 s[4:5], s[52:53]
	s_xor_b64 s[4:5], exec, s[4:5]
	v_fma_f32 v52, -v15, v15, 1.0
	s_andn2_saveexec_b64 s[4:5], s[4:5]
	v_pk_mul_f32 v[52:53], v[14:15], s[88:89] op_sel_hi:[0,1]
	v_add_f32_e32 v53, 1.0, v53
	v_fma_f32 v52, v52, v53, 1.0
	v_mul_f32_e64 v52, v52, -v14
	s_or_b64 exec, exec, s[4:5]
	v_add_f32_e32 v14, v19, v55
	v_mul_f32_e32 v14, 0xbfb8aa3b, v14
	v_exp_f32_e32 v14, v14
	v_max_f32_e32 v52, 0, v52
	v_sqrt_f32_e32 v52, v52
	v_add_f32_e32 v14, 1.0, v14
	v_rcp_f32_e32 v14, v14
	s_waitcnt lgkmcnt(0)
	v_lshlrev_b32_e32 v13, 16, v13
	v_add_u32_e32 v145, 0x4c, v72
	v_add_u32_e32 v137, 0x8800, v114
	v_mul_f32_e32 v14, v14, v52
	v_mul_f32_e32 v13, v14, v13
	v_add_u32_e32 v138, 0xa800, v114
	ds_write2st64_b32 v145, v15, v13 offset0:136 offset1:169
	s_waitcnt lgkmcnt(0)
	s_barrier
; __device__ __forceinline__ float bf2f(bf16_t v) { return __uint_as_float(((unsigned)v) << 16); }
; __device__ __forceinline__ bf16_t f2bf(float f) { return (bf16_t)(cvt_pk_bf16(f, 0.f) & 0xffffu); }
; __device__ __forceinline__ float siluf_(float x) { return x * __builtin_amdgcn_rcpf(1.f + __expf(-x)); }
; __device__ __forceinline__ void rglru_unit(const Params& p, const WS& ws, int j, int u, bool dry = false) {
;     ...
;   auto flush_y = [&]() {
;     if (ypend_t0 >= 0) {
; #pragma unroll
;       for (int i = 0; i < 8; ++i) {
;         const int t = ypend_t0 + 8 * ssg + i;
;         if (t < T_ && !dry) ws.GA[(size_t)(b * T_ + t) * 1024 + 128 * g + 32 * jq + sc] = ypend[i];
;       }
;     }
;   };
;   auto body = [&](int tile, u32x4 (&xin)[4], bf16_t (&gav)[8]) {
;     const int t0 = 64 * tile;
; #pragma unroll
;     for (int i = 0; i < 4; ++i) {
;       const int ci = tid + 256 * i; const int row = ci >> 4, ch = ci & 15;
;       *(u32x4*)(XC + row * 136 + 8 * ch) = xin[i];
;     }
;     float gcur[8];
; #pragma unroll
;     for (int i = 0; i < 8; ++i) gcur[i] = bf2f(gav[i]);
;     __syncthreads();
;     flush_y();
;     if (tile + 2 < 33) prefetch(tile + 2, xin, gav);
;     ...
;     {
;       float A = 1.f, Hh = 0.f;
; #pragma unroll
;       for (int i = 0; i < 8; ++i) {
;         const float a = AUa[(8 * ssg + i) * 33 + sc], uu = AUu[(8 * ssg + i) * 33 + sc];
;         Hh = a * Hh + uu; A *= a;
;       }
;       SEGA[ssg * 32 + sc] = A; SEGH[ssg * 32 + sc] = Hh;
;     }
;     __syncthreads();
;     float hin = CARRY[sc];
; #pragma unroll
;     for (int s2 = 0; s2 < 7; ++s2)
;       if (s2 < ssg) hin = SEGA[s2 * 32 + sc] * hin + SEGH[s2 * 32 + sc];
;     __syncthreads();
;     {
;       float h = hin;
; #pragma unroll
;       for (int i = 0; i < 8; ++i) {
;         const float a = AUa[(8 * ssg + i) * 33 + sc], uu = AUu[(8 * ssg + i) * 33 + sc];
;         h = a * h + uu;
;         const int t = t0 + 8 * ssg + i;
;         ypend[i] = f2bf(h * siluf_(gcur[i]));
;       }
;       if (ssg == 7) CARRY[sc] = h;
;       ypend_t0 = t0;
	ds_read2_b32 v[14:15], v137 offset1:33
	ds_read2_b32 v[52:53], v138 offset0:64 offset1:97
	v_add_u32_e32 v140, 0xac00, v114
	ds_read2_b32 v[204:205], v137 offset0:66 offset1:99
	ds_read2_b32 v[54:55], v138 offset0:130 offset1:163
	ds_read2_b32 v[206:207], v137 offset0:132 offset1:165
	ds_read2_b32 v[244:245], v138 offset0:196 offset1:229
	ds_read2_b32 v[208:209], v137 offset0:198 offset1:231
	ds_read2_b32 v[246:247], v140 offset0:6 offset1:39
	s_waitcnt lgkmcnt(6)
	v_fma_f32 v13, 0, v14, v52
	v_fmac_f32_e32 v53, v13, v15
	v_mul_f32_e32 v13, v14, v15
	s_waitcnt lgkmcnt(4)
	v_mul_f32_e32 v13, v13, v204
	v_fma_f32 v52, v53, v204, v54
	v_fmac_f32_e32 v55, v52, v205
	v_mul_f32_e32 v13, v13, v205
	s_waitcnt lgkmcnt(2)
	v_mul_f32_e32 v13, v13, v206
	v_fma_f32 v244, v55, v206, v244
	v_fmac_f32_e32 v245, v244, v207
	v_mul_f32_e32 v13, v13, v207
	s_waitcnt lgkmcnt(0)
	v_mul_f32_e32 v13, v13, v208
	v_fma_f32 v245, v245, v208, v246
	v_fmac_f32_e32 v247, v245, v209
	v_mul_f32_e32 v13, v13, v209
	ds_write2st64_b32 v78, v13, v247 offset0:202 offset1:206
	s_waitcnt lgkmcnt(0)
	s_barrier
	ds_read_b32 v13, v115 offset:53760
	v_add_u32_e32 v143, 0x80, v115
	ds_read2st64_b32 v[204:205], v115 offset0:202 offset1:206
	ds_read2st64_b32 v[206:207], v143 offset0:202 offset1:206
	ds_read2st64_b32 v[208:209], v115 offset0:203 offset1:207
	ds_read2st64_b32 v[244:245], v143 offset0:203 offset1:207
	ds_read2st64_b32 v[246:247], v115 offset0:204 offset1:208
	ds_read2st64_b32 v[248:249], v143 offset0:204 offset1:208
	ds_read2st64_b32 v[250:251], v115 offset0:205 offset1:209
	s_waitcnt lgkmcnt(6)
	v_fma_f32 v14, v13, v204, v205
	v_cndmask_b32_e32 v13, v13, v14, vcc
	s_waitcnt lgkmcnt(5)
	v_fma_f32 v14, v13, v206, v207
	v_cndmask_b32_e64 v13, v13, v14, s[38:39]
	s_waitcnt lgkmcnt(4)
	v_fma_f32 v14, v13, v208, v209
	v_cndmask_b32_e64 v13, v13, v14, s[40:41]
	s_waitcnt lgkmcnt(3)
	v_fma_f32 v14, v13, v244, v245
	v_cndmask_b32_e64 v13, v13, v14, s[42:43]
	s_waitcnt lgkmcnt(2)
	v_fma_f32 v14, v13, v246, v247
	v_cndmask_b32_e64 v13, v13, v14, s[44:45]
	s_waitcnt lgkmcnt(1)
	v_fma_f32 v14, v13, v248, v249
	v_cndmask_b32_e64 v13, v13, v14, s[46:47]
	s_waitcnt lgkmcnt(0)
	v_fma_f32 v14, v13, v250, v251
	v_cndmask_b32_e64 v13, v13, v14, s[48:49]
.LBB0_1454:
.LBB0_1455:
.LBB0_1456:
.LBB0_1457:
.LBB0_1458:
.LBB0_1459:
.LBB0_1460:
	s_or_b64 exec, exec, s[4:5]
	s_waitcnt lgkmcnt(0)
	s_barrier
	ds_read2_b32 v[204:205], v137 offset1:33
	ds_read2_b32 v[56:57], v138 offset0:64 offset1:97
	ds_read2_b32 v[206:207], v137 offset0:66 offset1:99
	ds_read2_b32 v[54:55], v138 offset0:130 offset1:163
	ds_read2_b32 v[208:209], v137 offset0:132 offset1:165
	ds_read2_b32 v[52:53], v138 offset0:196 offset1:229
	ds_read2_b32 v[58:59], v137 offset0:198 offset1:231
	ds_read2_b32 v[244:245], v140 offset0:6 offset1:39
	s_waitcnt lgkmcnt(6)
	v_fma_f32 v56, v13, v204, v56
	v_fmac_f32_e32 v57, v56, v205
	s_waitcnt lgkmcnt(4)
	v_fma_f32 v54, v57, v206, v54
	v_fmac_f32_e32 v55, v54, v207
	s_waitcnt lgkmcnt(2)
	v_fma_f32 v52, v55, v208, v52
	v_fmac_f32_e32 v53, v52, v209
	s_waitcnt lgkmcnt(0)
	v_fma_f32 v13, v53, v58, v244
	v_fma_f32 v15, v13, v59, v245
	s_and_saveexec_b64 s[4:5], s[50:51]
	ds_write_b32 v115, v15 offset:53760
	s_or_b64 exec, exec, s[4:5]
	v_lshlrev_b32_e32 v14, 16, v120
	v_mul_f32_e32 v58, 0xbfb8aa3b, v14
	v_exp_f32_e32 v58, v58
	v_lshlrev_b32_e32 v59, 16, v119
	v_lshlrev_b32_e32 v60, 16, v122
	v_lshlrev_b32_e32 v61, 16, v121
	v_add_f32_e32 v58, 1.0, v58
	v_rcp_f32_e32 v58, v58
	v_lshlrev_b32_e32 v62, 16, v124
	v_lshlrev_b32_e32 v63, 16, v123
	v_lshlrev_b32_e32 v64, 16, v128
	v_mul_f32_e32 v14, v58, v14
	v_mul_f32_e32 v14, v14, v56
	v_cvt_pk_bf16_f32 v58, v14, s0
	v_mul_f32_e32 v14, 0xbfb8aa3b, v59
	v_exp_f32_e32 v14, v14
	v_lshlrev_b32_e32 v65, 16, v127
	s_cmp_gt_u32 s7, 32
	v_add_f32_e32 v14, 1.0, v14
	v_rcp_f32_e32 v14, v14
	s_nop 0
	v_mul_f32_e32 v14, v14, v59
	v_mul_f32_e32 v14, v14, v57
	v_cvt_pk_bf16_f32 v59, v14, s0
	v_mul_f32_e32 v14, 0xbfb8aa3b, v60
	v_exp_f32_e32 v14, v14
	s_nop 0
	v_add_f32_e32 v14, 1.0, v14
	v_rcp_f32_e32 v14, v14
	s_nop 0
	v_mul_f32_e32 v14, v14, v60
	v_mul_f32_e32 v14, v14, v54
	v_cvt_pk_bf16_f32 v56, v14, s0
	v_mul_f32_e32 v14, 0xbfb8aa3b, v61
	v_exp_f32_e32 v14, v14
	s_nop 0
	v_add_f32_e32 v14, 1.0, v14
	v_rcp_f32_e32 v14, v14
	s_nop 0
	v_mul_f32_e32 v14, v14, v61
	v_mul_f32_e32 v14, v14, v55
	v_cvt_pk_bf16_f32 v57, v14, s0
	v_mul_f32_e32 v14, 0xbfb8aa3b, v62
	v_exp_f32_e32 v14, v14
	s_nop 0
	v_add_f32_e32 v14, 1.0, v14
	v_rcp_f32_e32 v14, v14
	s_nop 0
	v_mul_f32_e32 v14, v14, v62
	v_mul_f32_e32 v14, v14, v52
	v_cvt_pk_bf16_f32 v54, v14, s0
	v_mul_f32_e32 v14, 0xbfb8aa3b, v63
	v_exp_f32_e32 v14, v14
	s_nop 0
	v_add_f32_e32 v14, 1.0, v14
	v_rcp_f32_e32 v14, v14
	s_nop 0
	v_mul_f32_e32 v14, v14, v63
	v_mul_f32_e32 v14, v14, v53
	v_cvt_pk_bf16_f32 v55, v14, s0
	v_mul_f32_e32 v14, 0xbfb8aa3b, v64
	v_exp_f32_e32 v14, v14
	s_nop 0
	v_add_f32_e32 v14, 1.0, v14
	v_rcp_f32_e32 v14, v14
	s_nop 0
	v_mul_f32_e32 v14, v14, v64
	v_mul_f32_e32 v13, v14, v13
	v_cvt_pk_bf16_f32 v14, v13, s0
	v_mul_f32_e32 v13, 0xbfb8aa3b, v65
	v_exp_f32_e32 v13, v13
	s_nop 0
	v_add_f32_e32 v13, 1.0, v13
	v_rcp_f32_e32 v13, v13
	s_nop 0
	v_mul_f32_e32 v13, v13, v65
	v_mul_f32_e32 v13, v13, v15
	v_cvt_pk_bf16_f32 v15, v13, s0
	s_cbranch_scc1 .LBB0_1554
	v_add_u32_e32 v60, s6, v83
	v_cmp_gt_i32_e64 s[52:53], s15, v60
	v_add_u32_e32 v52, s6, v69
	s_waitcnt vmcnt(8)
	ds_write_b128 v106, v[36:39]
	ds_write_b128 v107, v[40:43]
	ds_write_b128 v109, v[44:47]
	ds_write_b128 v110, v[48:51]
	s_waitcnt lgkmcnt(0)
	s_barrier
	s_cmpk_gt_i32 s6, 0x7d0
	s_cbranch_scc1 .Lrg_fslow2
	s_mov_b64 s[4:5], 0x1000
	v_ashrrev_i32_e32 v53, 31, v52
	v_lshlrev_b64 v[62:63], 11, v[52:53]
	v_lshl_add_u64 v[62:63], v[74:75], 0, v[62:63]
	global_store_short v[62:63], v58, off
	global_store_short v[62:63], v59, off offset:2048
	v_lshl_add_u64 v[62:63], v[62:63], 0, s[4:5]
	global_store_short v[62:63], v56, off
	global_store_short v[62:63], v57, off offset:2048
	v_lshl_add_u64 v[62:63], v[62:63], 0, s[4:5]
	global_store_short v[62:63], v54, off
	global_store_short v[62:63], v55, off offset:2048
	v_lshl_add_u64 v[62:63], v[62:63], 0, s[4:5]
	global_store_short v[62:63], v14, off
	global_store_short v[62:63], v15, off offset:2048
	s_branch .Lrg_fjoin2

; __device__ __forceinline__ float bf2f(bf16_t v) { return __uint_as_float(((unsigned)v) << 16); }
; __device__ __forceinline__ float sigmoidf_(float x) { return __builtin_amdgcn_rcpf(1.f + __expf(-x)); }
; #define MFMA16(a, b, c) __builtin_amdgcn_mfma_f32_16x16x32_bf16((a), (b), (c), 0, 0, 0)
; __device__ __forceinline__ void rglru_unit(const Params& p, const WS& ws, int j, int u, bool dry = false) {
;     ...
; #pragma unroll
;       for (int ks = 0; ks < 4; ++ks) {
;         const bf16x8 xf = *(const bf16x8*)(XC + (16 * w + lr) * 136 + 32 * ks + 8 * lq);
; #pragma unroll
;         for (int gate = 0; gate < 2; ++gate)
; #pragma unroll
;           for (int mt = 0; mt < 2; ++mt) {
;             const bf16x8 wf = *(const bf16x8*)(WG + (gate * 32 + 16 * mt + lr) * 136 + 32 * ks + 8 * lq);
;             ga_[gate][mt] = MFMA16(wf, xf, ga_[gate][mt]);
;           }
;       }
;       const int tok = 16 * w + lr;
; #pragma unroll
;       for (int mt = 0; mt < 2; ++mt)
; #pragma unroll
;         for (int jj = 0; jj < 4; ++jj) {
;           const int n = 16 * mt + 4 * lq + jj;
;           const float xcv = bf2f(XC[tok * 136 + 32 * jq + n]);
;           const float r = sigmoidf_(ga_[0][mt][jj] + ba[mt][jj]);
;           const float ig = sigmoidf_(ga_[1][mt][jj] + bx[mt][jj]);
;           const float la = -r * sp[mt][jj];
;           const float a = __expf(la);
;           const float x2 = 2.f * la;
;           const float om = x2 > -0.02f ? -x2 * (1.f + 0.5f * x2 * (1.f + x2 * (1.f / 3.f))) : 1.f - a * a;
;           const float mult = __builtin_amdgcn_sqrtf(fmaxf(om, 0.f));
;           AUa[tok * 33 + n] = a;
;           AUu[tok * 33 + n] = mult * ig * xcv;
;         }
.LBB0_1505:
	ds_read_b128 v[52:55], v111
	ds_read_b128 v[56:59], v112 offset:17408
	ds_read_b128 v[60:63], v112 offset:21760
	ds_read_b128 v[64:67], v112 offset:26112
	ds_read_b128 v[120:123], v112 offset:30464
	ds_read_b128 v[212:215], v111 offset:64
	ds_read_b128 v[216:219], v111 offset:128
	ds_read_b128 v[220:223], v111 offset:192
	ds_read_b128 v[224:227], v112 offset:17472
	ds_read_b128 v[228:231], v112 offset:21824
	ds_read_b128 v[232:235], v112 offset:26176
	ds_read_b128 v[244:247], v112 offset:30528
	ds_read_b128 v[248:251], v112 offset:17536
	ds_read_b128 v[252:255], v112 offset:21888
	s_waitcnt lgkmcnt(12)
	v_mfma_f32_16x16x32_bf16 v[56:59], v[56:59], v[52:55], 0
	s_waitcnt lgkmcnt(11)
	v_mfma_f32_16x16x32_bf16 v[60:63], v[60:63], v[52:55], 0
	s_waitcnt lgkmcnt(10)
	v_mfma_f32_16x16x32_bf16 v[64:67], v[64:67], v[52:55], 0
	s_waitcnt lgkmcnt(9)
	v_mfma_f32_16x16x32_bf16 v[52:55], v[120:123], v[52:55], 0
	s_nop 0
	s_nop 0
	s_waitcnt lgkmcnt(5)
	v_mfma_f32_16x16x32_bf16 v[56:59], v[224:227], v[212:215], v[56:59]
	ds_read_b128 v[224:227], v112 offset:26240
	s_nop 0
	s_waitcnt lgkmcnt(5)
	v_mfma_f32_16x16x32_bf16 v[60:63], v[228:231], v[212:215], v[60:63]
	ds_read_b128 v[228:231], v112 offset:30592
	s_nop 0
	s_waitcnt lgkmcnt(5)
	v_mfma_f32_16x16x32_bf16 v[64:67], v[232:235], v[212:215], v[64:67]
	ds_read_b128 v[232:235], v112 offset:17600
	s_nop 0
	s_waitcnt lgkmcnt(5)
	v_mfma_f32_16x16x32_bf16 v[52:55], v[244:247], v[212:215], v[52:55]
	ds_read_b128 v[244:247], v112 offset:21952
	s_nop 0
	s_nop 0
	s_waitcnt lgkmcnt(5)
	v_mfma_f32_16x16x32_bf16 v[56:59], v[248:251], v[216:219], v[56:59]
	ds_read_b128 v[248:251], v112 offset:26304
	s_nop 0
	s_waitcnt lgkmcnt(5)
	v_mfma_f32_16x16x32_bf16 v[60:63], v[252:255], v[216:219], v[60:63]
	ds_read_b128 v[252:255], v112 offset:30656
	s_nop 0
	s_waitcnt lgkmcnt(5)
	v_mfma_f32_16x16x32_bf16 v[154:157], v[224:227], v[216:219], v[64:67]
	s_nop 2
	s_nop 0
	s_waitcnt lgkmcnt(4)
	v_mfma_f32_16x16x32_bf16 v[52:55], v[228:231], v[216:219], v[52:55]
	s_nop 0
	s_nop 0
	ds_read_u16 v15, v113
	s_waitcnt lgkmcnt(4)
	v_mfma_f32_16x16x32_bf16 v[64:67], v[232:235], v[220:223], v[56:59]
	s_nop 2
	s_nop 0
	s_waitcnt lgkmcnt(3)
	v_mfma_f32_16x16x32_bf16 v[56:59], v[244:247], v[220:223], v[60:63]
	s_nop 2
	s_nop 0
	v_add_f32_e32 v14, v0, v64
	v_mul_f32_e32 v14, 0xbfb8aa3b, v14
	v_exp_f32_e32 v14, v14
	s_waitcnt lgkmcnt(2)
	v_mfma_f32_16x16x32_bf16 v[60:63], v[248:251], v[220:223], v[154:157]
	s_nop 2
	s_nop 0
	v_add_f32_e32 v14, 1.0, v14
	v_rcp_f32_e64 v14, -v14
	s_waitcnt lgkmcnt(0)
	v_mfma_f32_16x16x32_bf16 v[52:55], v[252:255], v[220:223], v[52:55]
	v_mul_f32_e32 v14, v89, v14
	v_mul_f32_e32 v64, 0x3fb8aa3b, v14
	v_exp_f32_e32 v64, v64
	v_add_f32_e32 v14, v14, v14
	v_cmp_nlt_f32_e64 s[52:53], s29, v14
	s_and_saveexec_b64 s[4:5], s[52:53]
	s_xor_b64 s[4:5], exec, s[4:5]
	v_fma_f32 v119, -v64, v64, 1.0
	s_andn2_saveexec_b64 s[4:5], s[4:5]
	v_pk_mul_f32 v[120:121], v[14:15], s[88:89] op_sel_hi:[0,1]
	v_add_f32_e32 v119, 1.0, v121
	v_fma_f32 v119, v120, v119, 1.0
	v_mul_f32_e64 v119, v119, -v14
	s_or_b64 exec, exec, s[4:5]
	v_add_f32_e32 v14, v8, v60
	v_add_f32_e32 v65, v1, v65
	v_mul_f32_e32 v14, 0xbfb8aa3b, v14
	v_mul_f32_e32 v65, 0xbfb8aa3b, v65
	v_exp_f32_e32 v14, v14
	v_exp_f32_e32 v65, v65
	v_max_f32_e32 v60, 0, v119
	v_add_f32_e32 v14, 1.0, v14
	v_add_f32_e32 v65, 1.0, v65
	v_rcp_f32_e32 v14, v14
	v_sqrt_f32_e32 v60, v60
	v_rcp_f32_e64 v65, -v65
	v_lshlrev_b32_e32 v15, 16, v15
	v_mul_f32_e32 v14, v14, v60
	v_mul_f32_e32 v65, v93, v65
	v_mul_f32_e32 v14, v14, v15
	ds_read_u16 v60, v113 offset:2
	v_mul_f32_e32 v15, 0x3fb8aa3b, v65
	v_exp_f32_e32 v15, v15
	ds_write2st64_b32 v72, v64, v14 offset0:136 offset1:169
	v_add_f32_e32 v14, v65, v65
	v_cmp_nlt_f32_e64 s[52:53], s29, v14
	s_and_saveexec_b64 s[4:5], s[52:53]
	s_xor_b64 s[4:5], exec, s[4:5]
	v_fma_f32 v64, -v15, v15, 1.0
	s_andn2_saveexec_b64 s[4:5], s[4:5]
	v_pk_mul_f32 v[64:65], v[14:15], s[88:89] op_sel_hi:[0,1]
	v_add_f32_e32 v65, 1.0, v65
	v_fma_f32 v64, v64, v65, 1.0
	v_mul_f32_e64 v64, v64, -v14
	s_or_b64 exec, exec, s[4:5]
	v_add_f32_e32 v14, v9, v61
	v_max_f32_e32 v61, v64, v64
	v_add_f32_e32 v64, v2, v66
	v_mul_f32_e32 v14, 0xbfb8aa3b, v14
	v_mul_f32_e32 v64, 0xbfb8aa3b, v64
	v_exp_f32_e32 v14, v14
	v_exp_f32_e32 v64, v64
	v_max_f32_e32 v61, 0, v61
	v_sqrt_f32_e32 v61, v61
	v_add_f32_e32 v14, 1.0, v14
	v_add_f32_e32 v64, 1.0, v64
	v_rcp_f32_e32 v14, v14
	v_rcp_f32_e64 v64, -v64
	s_waitcnt lgkmcnt(1)
	v_lshlrev_b32_e32 v60, 16, v60
	v_mul_f32_e32 v14, v14, v61
	v_mul_f32_e32 v64, v95, v64
	v_mul_f32_e32 v14, v14, v60
	ds_read_u16 v61, v113 offset:4
	v_mul_f32_e32 v60, 0x3fb8aa3b, v64
	v_exp_f32_e32 v60, v60
	ds_write2st64_b32 v135, v15, v14 offset0:136 offset1:169
	v_add_f32_e32 v14, v64, v64
	v_cmp_nlt_f32_e64 s[52:53], s29, v14
	s_and_saveexec_b64 s[4:5], s[52:53]
	s_xor_b64 s[4:5], exec, s[4:5]
	v_fma_f32 v15, -v60, v60, 1.0
	s_andn2_saveexec_b64 s[4:5], s[4:5]
	v_pk_mul_f32 v[64:65], v[14:15], s[88:89] op_sel_hi:[0,1]
	v_add_f32_e32 v15, 1.0, v65
	v_fma_f32 v15, v64, v15, 1.0
	v_mul_f32_e64 v15, v15, -v14
	s_or_b64 exec, exec, s[4:5]
	v_add_f32_e32 v14, v10, v62
	v_add_f32_e32 v62, v3, v67
	v_mul_f32_e32 v14, 0xbfb8aa3b, v14
	v_mul_f32_e32 v62, 0xbfb8aa3b, v62
	v_exp_f32_e32 v14, v14
	v_exp_f32_e32 v62, v62
	v_max_f32_e32 v15, 0, v15
	v_add_f32_e32 v14, 1.0, v14
	v_add_f32_e32 v62, 1.0, v62
	v_rcp_f32_e32 v14, v14
	v_sqrt_f32_e32 v15, v15
	v_rcp_f32_e64 v62, -v62
	s_waitcnt lgkmcnt(1)
; __device__ __forceinline__ float bf2f(bf16_t v) { return __uint_as_float(((unsigned)v) << 16); }
; __device__ __forceinline__ float sigmoidf_(float x) { return __builtin_amdgcn_rcpf(1.f + __expf(-x)); }
; __device__ __forceinline__ void rglru_unit(const Params& p, const WS& ws, int j, int u, bool dry = false) {
;     ...
;       const int tok = 16 * w + lr;
; #pragma unroll
;       for (int mt = 0; mt < 2; ++mt)
; #pragma unroll
;         for (int jj = 0; jj < 4; ++jj) {
;           const int n = 16 * mt + 4 * lq + jj;
;           const float xcv = bf2f(XC[tok * 136 + 32 * jq + n]);
;           const float r = sigmoidf_(ga_[0][mt][jj] + ba[mt][jj]);
;           const float ig = sigmoidf_(ga_[1][mt][jj] + bx[mt][jj]);
;           const float la = -r * sp[mt][jj];
;           const float a = __expf(la);
;           const float x2 = 2.f * la;
;           const float om = x2 > -0.02f ? -x2 * (1.f + 0.5f * x2 * (1.f + x2 * (1.f / 3.f))) : 1.f - a * a;
;           const float mult = __builtin_amdgcn_sqrtf(fmaxf(om, 0.f));
;           AUa[tok * 33 + n] = a;
;           AUu[tok * 33 + n] = mult * ig * xcv;
;         }
;     }
;     __syncthreads();
	v_lshlrev_b32_e32 v61, 16, v61
	v_mul_f32_e32 v14, v14, v15
	v_mul_f32_e32 v62, v96, v62
	v_mul_f32_e32 v14, v14, v61
	ds_read_u16 v61, v113 offset:6
	v_mul_f32_e32 v15, 0x3fb8aa3b, v62
	v_exp_f32_e32 v15, v15
	ds_write2st64_b32 v136, v60, v14 offset0:136 offset1:169
	v_add_f32_e32 v14, v62, v62
	v_cmp_nlt_f32_e64 s[52:53], s29, v14
	s_and_saveexec_b64 s[4:5], s[52:53]
	s_xor_b64 s[4:5], exec, s[4:5]
	v_fma_f32 v60, -v15, v15, 1.0
	s_andn2_saveexec_b64 s[4:5], s[4:5]
	v_pk_mul_f32 v[64:65], v[14:15], s[88:89] op_sel_hi:[0,1]
	v_add_f32_e32 v60, 1.0, v65
	v_fma_f32 v60, v64, v60, 1.0
	v_mul_f32_e64 v60, v60, -v14
	s_or_b64 exec, exec, s[4:5]
	v_add_f32_e32 v14, v11, v63
	v_mul_f32_e32 v14, 0xbfb8aa3b, v14
	v_add_f32_e32 v56, v4, v56
	v_exp_f32_e32 v14, v14
	v_mul_f32_e32 v56, 0xbfb8aa3b, v56
	v_exp_f32_e32 v56, v56
	v_add_f32_e32 v14, 1.0, v14
	v_max_f32_e32 v60, 0, v60
	v_rcp_f32_e32 v14, v14
	v_sqrt_f32_e32 v60, v60
	v_add_f32_e32 v56, 1.0, v56
	v_rcp_f32_e64 v56, -v56
	s_waitcnt lgkmcnt(1)
	v_lshlrev_b32_e32 v61, 16, v61
	v_mul_f32_e32 v14, v14, v60
	v_mul_f32_e32 v14, v14, v61
	v_mul_f32_e32 v61, v97, v56
	ds_read_u16 v60, v113 offset:32
	v_mul_f32_e32 v56, 0x3fb8aa3b, v61
	v_exp_f32_e32 v56, v56
	ds_write2st64_b32 v139, v15, v14 offset0:136 offset1:169
	v_add_f32_e32 v14, v61, v61
	v_cmp_nlt_f32_e64 s[52:53], s29, v14
	s_and_saveexec_b64 s[4:5], s[52:53]
	s_xor_b64 s[4:5], exec, s[4:5]
	v_fma_f32 v15, -v56, v56, 1.0
	s_andn2_saveexec_b64 s[4:5], s[4:5]
	v_pk_mul_f32 v[62:63], v[14:15], s[88:89] op_sel_hi:[0,1]
	v_add_f32_e32 v15, 1.0, v63
	v_fma_f32 v15, v62, v15, 1.0
	v_mul_f32_e64 v15, v15, -v14
	s_or_b64 exec, exec, s[4:5]
	v_add_f32_e32 v14, v16, v52
	v_mul_f32_e32 v14, 0xbfb8aa3b, v14
	v_add_f32_e32 v52, v5, v57
	v_exp_f32_e32 v14, v14
	v_mul_f32_e32 v52, 0xbfb8aa3b, v52
	v_exp_f32_e32 v52, v52
	v_add_f32_e32 v14, 1.0, v14
	v_max_f32_e32 v15, 0, v15
	v_rcp_f32_e32 v14, v14
	v_sqrt_f32_e32 v15, v15
	v_add_f32_e32 v52, 1.0, v52
	s_waitcnt lgkmcnt(1)
	v_lshlrev_b32_e32 v57, 16, v60
	v_rcp_f32_e64 v60, -v52
	v_mul_f32_e32 v14, v14, v15
	v_mul_f32_e32 v14, v14, v57
	ds_read_u16 v52, v113 offset:34
	v_mul_f32_e32 v57, v98, v60
	v_mul_f32_e32 v15, 0x3fb8aa3b, v57
	v_exp_f32_e32 v15, v15
	ds_write2st64_b32 v141, v56, v14 offset0:136 offset1:169
	v_add_f32_e32 v14, v57, v57
	v_cmp_nlt_f32_e64 s[52:53], s29, v14
	s_and_saveexec_b64 s[4:5], s[52:53]
	s_xor_b64 s[4:5], exec, s[4:5]
	v_fma_f32 v56, -v15, v15, 1.0
	s_andn2_saveexec_b64 s[4:5], s[4:5]
	v_pk_mul_f32 v[56:57], v[14:15], s[88:89] op_sel_hi:[0,1]
	v_add_f32_e32 v57, 1.0, v57
	v_fma_f32 v56, v56, v57, 1.0
	v_mul_f32_e64 v56, v56, -v14
	s_or_b64 exec, exec, s[4:5]
	v_add_f32_e32 v14, v17, v53
	v_max_f32_e32 v53, v56, v56
	v_add_f32_e32 v56, v6, v58
	v_mul_f32_e32 v14, 0xbfb8aa3b, v14
	v_mul_f32_e32 v56, 0xbfb8aa3b, v56
	v_exp_f32_e32 v14, v14
	v_exp_f32_e32 v56, v56
	v_max_f32_e32 v53, 0, v53
	v_sqrt_f32_e32 v53, v53
	v_add_f32_e32 v14, 1.0, v14
	v_add_f32_e32 v56, 1.0, v56
	v_rcp_f32_e32 v14, v14
	v_rcp_f32_e64 v56, -v56
	s_waitcnt lgkmcnt(1)
	v_lshlrev_b32_e32 v52, 16, v52
	v_mul_f32_e32 v14, v14, v53
	v_mul_f32_e32 v56, v99, v56
	v_mul_f32_e32 v14, v14, v52
	ds_read_u16 v53, v113 offset:36
	v_mul_f32_e32 v52, 0x3fb8aa3b, v56
	v_exp_f32_e32 v52, v52
	ds_write2st64_b32 v142, v15, v14 offset0:136 offset1:169
	v_add_f32_e32 v14, v56, v56
	v_cmp_nlt_f32_e64 s[52:53], s29, v14
	s_and_saveexec_b64 s[4:5], s[52:53]
	s_xor_b64 s[4:5], exec, s[4:5]
	v_fma_f32 v15, -v52, v52, 1.0
	s_andn2_saveexec_b64 s[4:5], s[4:5]
	v_pk_mul_f32 v[56:57], v[14:15], s[88:89] op_sel_hi:[0,1]
	v_add_f32_e32 v15, 1.0, v57
	v_fma_f32 v15, v56, v15, 1.0
	v_mul_f32_e64 v15, v15, -v14
	s_or_b64 exec, exec, s[4:5]
	v_add_f32_e32 v14, v18, v54
	v_add_f32_e32 v54, v7, v59
	v_mul_f32_e32 v14, 0xbfb8aa3b, v14
	v_mul_f32_e32 v54, 0xbfb8aa3b, v54
	v_exp_f32_e32 v14, v14
	v_exp_f32_e32 v54, v54
	v_max_f32_e32 v15, 0, v15
	v_add_f32_e32 v14, 1.0, v14
	v_add_f32_e32 v54, 1.0, v54
	v_rcp_f32_e32 v14, v14
	v_sqrt_f32_e32 v15, v15
	v_rcp_f32_e64 v54, -v54
	s_waitcnt lgkmcnt(1)
	v_lshlrev_b32_e32 v53, 16, v53
	v_mul_f32_e32 v14, v14, v15
	v_mul_f32_e32 v54, v105, v54
	v_mul_f32_e32 v14, v14, v53
	ds_read_u16 v53, v113 offset:38
	v_mul_f32_e32 v15, 0x3fb8aa3b, v54
	v_exp_f32_e32 v15, v15
	ds_write2st64_b32 v144, v52, v14 offset0:136 offset1:169
	v_add_f32_e32 v14, v54, v54
	v_cmp_nlt_f32_e64 s[52:53], s29, v14
	s_and_saveexec_b64 s[4:5], s[52:53]
	s_xor_b64 s[4:5], exec, s[4:5]
	v_fma_f32 v52, -v15, v15, 1.0
	s_andn2_saveexec_b64 s[4:5], s[4:5]
	v_pk_mul_f32 v[56:57], v[14:15], s[88:89] op_sel_hi:[0,1]
	v_add_f32_e32 v52, 1.0, v57
	v_fma_f32 v52, v56, v52, 1.0
	v_mul_f32_e64 v52, v52, -v14
	s_or_b64 exec, exec, s[4:5]
	s_waitcnt lgkmcnt(1)
	v_lshlrev_b32_e32 v14, 16, v53
	v_add_f32_e32 v53, v19, v55
	v_mul_f32_e32 v53, 0xbfb8aa3b, v53
	v_exp_f32_e32 v53, v53
	v_max_f32_e32 v52, 0, v52
	v_sqrt_f32_e32 v52, v52
	v_add_f32_e32 v53, 1.0, v53
	v_rcp_f32_e32 v53, v53
	s_nop 0
	v_mul_f32_e32 v52, v53, v52
	v_mul_f32_e32 v14, v52, v14
	ds_write2st64_b32 v145, v15, v14 offset0:136 offset1:169
	s_waitcnt lgkmcnt(0)
	s_barrier
; __device__ __forceinline__ bf16_t f2bf(float f) { return (bf16_t)(cvt_pk_bf16(f, 0.f) & 0xffffu); }
; __device__ __forceinline__ float siluf_(float x) { return x * __builtin_amdgcn_rcpf(1.f + __expf(-x)); }
; __device__ __forceinline__ void rglru_unit(const Params& p, const WS& ws, int j, int u, bool dry = false) {
;     ...
;     {
;       float A = 1.f, Hh = 0.f;
; #pragma unroll
;       for (int i = 0; i < 8; ++i) {
;         const float a = AUa[(8 * ssg + i) * 33 + sc], uu = AUu[(8 * ssg + i) * 33 + sc];
;         Hh = a * Hh + uu; A *= a;
;       }
;       SEGA[ssg * 32 + sc] = A; SEGH[ssg * 32 + sc] = Hh;
;     }
;     __syncthreads();
;     float hin = CARRY[sc];
; #pragma unroll
;     for (int s2 = 0; s2 < 7; ++s2)
;       if (s2 < ssg) hin = SEGA[s2 * 32 + sc] * hin + SEGH[s2 * 32 + sc];
;     __syncthreads();
;     {
;       float h = hin;
; #pragma unroll
;       for (int i = 0; i < 8; ++i) {
;         const float a = AUa[(8 * ssg + i) * 33 + sc], uu = AUu[(8 * ssg + i) * 33 + sc];
;         h = a * h + uu;
;         const int t = t0 + 8 * ssg + i;
;         ypend[i] = f2bf(h * siluf_(gcur[i]));
;       }
;       if (ssg == 7) CARRY[sc] = h;
;       ypend_t0 = t0;
	ds_read2_b32 v[14:15], v137 offset1:33
	ds_read2_b32 v[52:53], v138 offset0:64 offset1:97
	s_nop 0
	ds_read2_b32 v[204:205], v137 offset0:66 offset1:99
	ds_read2_b32 v[54:55], v138 offset0:130 offset1:163
	ds_read2_b32 v[206:207], v137 offset0:132 offset1:165
	ds_read2_b32 v[244:245], v138 offset0:196 offset1:229
	ds_read2_b32 v[208:209], v137 offset0:198 offset1:231
	ds_read2_b32 v[246:247], v140 offset0:6 offset1:39
	s_waitcnt lgkmcnt(6)
	v_fma_f32 v52, 0, v14, v52
	v_fmac_f32_e32 v53, v52, v15
	v_mul_f32_e32 v52, v14, v15
	s_waitcnt lgkmcnt(4)
	v_fma_f32 v53, v53, v204, v54
	v_mul_f32_e32 v14, v52, v204
	v_fmac_f32_e32 v55, v53, v205
	v_mul_f32_e32 v54, v14, v205
	s_waitcnt lgkmcnt(2)
	v_fma_f32 v244, v55, v206, v244
	v_mul_f32_e32 v14, v54, v206
	v_fmac_f32_e32 v245, v244, v207
	v_mul_f32_e32 v52, v14, v207
	s_waitcnt lgkmcnt(0)
	v_fma_f32 v245, v245, v208, v246
	v_mul_f32_e32 v14, v52, v208
	v_fmac_f32_e32 v247, v245, v209
	v_mul_f32_e32 v14, v14, v209
	ds_write2st64_b32 v78, v14, v247 offset0:202 offset1:206
	s_waitcnt lgkmcnt(0)
	s_barrier
	ds_read_b32 v14, v115 offset:53760
	ds_read2st64_b32 v[204:205], v115 offset0:202 offset1:206
	ds_read2st64_b32 v[206:207], v143 offset0:202 offset1:206
	ds_read2st64_b32 v[208:209], v115 offset0:203 offset1:207
	ds_read2st64_b32 v[244:245], v143 offset0:203 offset1:207
	ds_read2st64_b32 v[246:247], v115 offset0:204 offset1:208
	ds_read2st64_b32 v[248:249], v143 offset0:204 offset1:208
	ds_read2st64_b32 v[250:251], v115 offset0:205 offset1:209
	s_waitcnt lgkmcnt(6)
	v_fma_f32 v52, v14, v204, v205
	v_cndmask_b32_e32 v14, v14, v52, vcc
	s_waitcnt lgkmcnt(5)
	v_fma_f32 v52, v14, v206, v207
	v_cndmask_b32_e64 v14, v14, v52, s[38:39]
	s_waitcnt lgkmcnt(4)
	v_fma_f32 v52, v14, v208, v209
	v_cndmask_b32_e64 v14, v14, v52, s[40:41]
	s_waitcnt lgkmcnt(3)
	v_fma_f32 v52, v14, v244, v245
	v_cndmask_b32_e64 v14, v14, v52, s[42:43]
	s_waitcnt lgkmcnt(2)
	v_fma_f32 v52, v14, v246, v247
	v_cndmask_b32_e64 v14, v14, v52, s[44:45]
	s_waitcnt lgkmcnt(1)
	v_fma_f32 v52, v14, v248, v249
	v_cndmask_b32_e64 v14, v14, v52, s[46:47]
	s_waitcnt lgkmcnt(0)
	v_fma_f32 v52, v14, v250, v251
	v_cndmask_b32_e64 v14, v14, v52, s[48:49]
.LBB0_1539:
.LBB0_1540:
.LBB0_1541:
.LBB0_1542:
.LBB0_1543:
.LBB0_1544:
.LBB0_1545:
	s_or_b64 exec, exec, s[4:5]
	s_waitcnt lgkmcnt(0)
	s_barrier
	ds_read2_b32 v[204:205], v137 offset1:33
	ds_read2_b32 v[56:57], v138 offset0:64 offset1:97
	ds_read2_b32 v[206:207], v137 offset0:66 offset1:99
	ds_read2_b32 v[54:55], v138 offset0:130 offset1:163
	ds_read2_b32 v[208:209], v137 offset0:132 offset1:165
	ds_read2_b32 v[52:53], v138 offset0:196 offset1:229
	ds_read2_b32 v[58:59], v137 offset0:198 offset1:231
	ds_read2_b32 v[244:245], v140 offset0:6 offset1:39
	s_waitcnt lgkmcnt(6)
	v_fma_f32 v56, v14, v204, v56
	v_fmac_f32_e32 v57, v56, v205
	s_waitcnt lgkmcnt(4)
	v_fma_f32 v54, v57, v206, v54
	v_fmac_f32_e32 v55, v54, v207
	s_waitcnt lgkmcnt(2)
	v_fma_f32 v52, v55, v208, v52
	v_fmac_f32_e32 v53, v52, v209
	s_waitcnt lgkmcnt(0)
	v_fma_f32 v14, v53, v58, v244
	v_fma_f32 v15, v14, v59, v245
	s_and_saveexec_b64 s[4:5], s[50:51]
	ds_write_b32 v115, v15 offset:53760
	s_or_b64 exec, exec, s[4:5]
	v_lshlrev_b32_e32 v58, 16, v86
	v_mul_f32_e32 v66, 0xbfb8aa3b, v58
	v_exp_f32_e32 v66, v66
	v_lshlrev_b32_e32 v59, 16, v85
	v_lshlrev_b32_e32 v60, 16, v88
	v_lshlrev_b32_e32 v61, 16, v87
	v_add_f32_e32 v66, 1.0, v66
	v_rcp_f32_e32 v66, v66
	v_lshlrev_b32_e32 v62, 16, v91
	v_lshlrev_b32_e32 v63, 16, v90
	v_lshlrev_b32_e32 v64, 16, v92
	v_mul_f32_e32 v58, v66, v58
	v_mul_f32_e32 v56, v58, v56
	v_cvt_pk_bf16_f32 v58, v56, s0
	v_mul_f32_e32 v56, 0xbfb8aa3b, v59
	v_exp_f32_e32 v56, v56
	v_lshlrev_b32_e32 v65, 16, v94
	s_add_i32 s4, s6, 64
	v_add_f32_e32 v56, 1.0, v56
	v_rcp_f32_e32 v56, v56
	s_nop 0
	v_mul_f32_e32 v56, v56, v59
	v_mul_f32_e32 v56, v56, v57
	v_cvt_pk_bf16_f32 v59, v56, s0
	v_mul_f32_e32 v56, 0xbfb8aa3b, v60
	v_exp_f32_e32 v56, v56
	s_nop 0
	v_add_f32_e32 v56, 1.0, v56
	v_rcp_f32_e32 v56, v56
	s_nop 0
	v_mul_f32_e32 v56, v56, v60
	v_mul_f32_e32 v54, v56, v54
	v_cvt_pk_bf16_f32 v56, v54, s0
	v_mul_f32_e32 v54, 0xbfb8aa3b, v61
	v_exp_f32_e32 v54, v54
	s_nop 0
	v_add_f32_e32 v54, 1.0, v54
	v_rcp_f32_e32 v54, v54
	s_nop 0
	v_mul_f32_e32 v54, v54, v61
	v_mul_f32_e32 v54, v54, v55
	v_cvt_pk_bf16_f32 v57, v54, s0
	v_mul_f32_e32 v54, 0xbfb8aa3b, v62
	v_exp_f32_e32 v54, v54
	s_nop 0
	v_add_f32_e32 v54, 1.0, v54
	v_rcp_f32_e32 v54, v54
	s_nop 0
	v_mul_f32_e32 v54, v54, v62
	v_mul_f32_e32 v52, v54, v52
	v_cvt_pk_bf16_f32 v54, v52, s0
	v_mul_f32_e32 v52, 0xbfb8aa3b, v63
	v_exp_f32_e32 v52, v52
	s_nop 0
	v_add_f32_e32 v52, 1.0, v52
	v_rcp_f32_e32 v52, v52
	s_nop 0
	v_mul_f32_e32 v52, v52, v63
	v_mul_f32_e32 v52, v52, v53
	v_cvt_pk_bf16_f32 v55, v52, s0
	v_mul_f32_e32 v52, 0xbfb8aa3b, v64
	v_exp_f32_e32 v52, v52
	s_nop 0
	v_add_f32_e32 v52, 1.0, v52
	v_rcp_f32_e32 v52, v52
	s_nop 0
	v_mul_f32_e32 v52, v52, v64
	v_mul_f32_e32 v14, v52, v14
	v_mul_f32_e32 v52, 0xbfb8aa3b, v65
	v_exp_f32_e32 v52, v52
	v_cvt_pk_bf16_f32 v14, v14, s0
	v_add_f32_e32 v52, 1.0, v52
	v_rcp_f32_e32 v52, v52
	s_nop 0
	v_mul_f32_e32 v52, v52, v65
	v_mul_f32_e32 v15, v52, v15
	v_cvt_pk_bf16_f32 v15, v15, s0
	s_branch .LBB0_1555
